# cache policy: final f32 output stores of P11 also non-temporal (on top of the non-temporal hidden-activation stores)
# speedup vs baseline: 1.0081x; 1.0020x over previous
.LBB0_1470:
	v_mov_b32_e32 v145, v149
	v_mov_b32_e32 v144, v148
	s_lshl_b32 s4, s22, 8
	s_add_i32 s4, s4, s37
	v_add_u32_e32 v144, s4, v144
	s_lshl_b32 s4, s45, 8
	s_ashr_i32 s5, s4, 31
	v_lshlrev_b32_e32 v146, 2, v145
	v_ashrrev_i32_e32 v147, 31, v146
	s_or_b64 s[4:5], s[4:5], s[6:7]
	v_ashrrev_i32_e32 v145, 31, v144
	v_lshl_add_u64 v[146:147], s[4:5], 0, v[146:147]
	v_lshlrev_b64 v[154:155], 10, v[144:145]
	v_lshl_add_u64 v[154:155], v[146:147], 0, v[154:155]
	v_lshl_add_u64 v[156:157], v[154:155], 1, s[8:9]
	global_load_dwordx2 v[158:159], v[156:157], off
	global_load_dwordx2 v[162:163], v[156:157], off offset:32
	global_load_dwordx2 v[164:165], v[156:157], off offset:256
	global_load_dwordx2 v[166:167], v[156:157], off offset:288
	v_lshl_add_u64 v[154:155], v[154:155], 2, s[76:77]
	s_and_b64 vcc, exec, s[0:1]
	s_mov_b64 s[0:1], -1
	s_waitcnt vmcnt(0)
	v_lshlrev_b32_e32 v160, 16, v158
	v_and_b32_e32 v161, 0xffff0000, v158
	v_lshlrev_b32_e32 v158, 16, v159
	v_and_b32_e32 v159, 0xffff0000, v159
	v_pk_fma_f32 v[126:127], v[126:127], 0.5, v[158:159] op_sel_hi:[1,0,1]
	v_pk_fma_f32 v[124:125], v[124:125], 0.5, v[160:161] op_sel_hi:[1,0,1]
	global_store_dwordx4 v[154:155], v[124:127], off nt
	s_nop 1
	v_lshlrev_b32_e32 v126, 16, v162
	v_and_b32_e32 v127, 0xffff0000, v162
	v_lshlrev_b32_e32 v124, 16, v163
	v_and_b32_e32 v125, 0xffff0000, v163
	v_pk_fma_f32 v[122:123], v[122:123], 0.5, v[124:125] op_sel_hi:[1,0,1]
	v_pk_fma_f32 v[120:121], v[120:121], 0.5, v[126:127] op_sel_hi:[1,0,1]
	global_store_dwordx4 v[154:155], v[120:123], off offset:64 nt
	s_nop 1
	v_lshlrev_b32_e32 v122, 16, v164
	v_and_b32_e32 v123, 0xffff0000, v164
	v_lshlrev_b32_e32 v120, 16, v165
	v_and_b32_e32 v121, 0xffff0000, v165
	v_pk_fma_f32 v[118:119], v[118:119], 0.5, v[120:121] op_sel_hi:[1,0,1]
	v_pk_fma_f32 v[116:117], v[116:117], 0.5, v[122:123] op_sel_hi:[1,0,1]
	global_store_dwordx4 v[154:155], v[116:119], off offset:512 nt
	s_nop 1
	v_lshlrev_b32_e32 v122, 16, v166
	v_add_u32_e32 v118, 16, v144
	v_ashrrev_i32_e32 v119, 31, v118
	v_lshlrev_b64 v[118:119], 10, v[118:119]
	v_and_b32_e32 v123, 0xffff0000, v166
	v_lshlrev_b32_e32 v116, 16, v167
	v_and_b32_e32 v117, 0xffff0000, v167
	v_lshl_add_u64 v[118:119], v[118:119], 0, v[146:147]
	v_pk_fma_f32 v[110:111], v[110:111], 0.5, v[116:117] op_sel_hi:[1,0,1]
	v_pk_fma_f32 v[108:109], v[108:109], 0.5, v[122:123] op_sel_hi:[1,0,1]
	v_lshl_add_u64 v[120:121], v[118:119], 1, s[8:9]
	global_store_dwordx4 v[154:155], v[108:111], off offset:576 nt
	global_load_dwordx2 v[108:109], v[120:121], off
	global_load_dwordx2 v[162:163], v[120:121], off offset:32
	global_load_dwordx2 v[164:165], v[120:121], off offset:256
	global_load_dwordx2 v[166:167], v[120:121], off offset:288
	v_lshl_add_u64 v[116:117], v[118:119], 2, s[76:77]
	s_waitcnt vmcnt(0)
	v_lshlrev_b32_e32 v118, 16, v108
	v_and_b32_e32 v119, 0xffff0000, v108
	v_lshlrev_b32_e32 v108, 16, v109
	v_and_b32_e32 v109, 0xffff0000, v109
	v_pk_fma_f32 v[110:111], v[114:115], 0.5, v[108:109] op_sel_hi:[1,0,1]
	v_pk_fma_f32 v[108:109], v[112:113], 0.5, v[118:119] op_sel_hi:[1,0,1]
	global_store_dwordx4 v[116:117], v[108:111], off nt
	s_nop 1
	v_lshlrev_b32_e32 v110, 16, v162
	v_and_b32_e32 v111, 0xffff0000, v162
	v_lshlrev_b32_e32 v108, 16, v163
	v_and_b32_e32 v109, 0xffff0000, v163
	v_pk_fma_f32 v[106:107], v[106:107], 0.5, v[108:109] op_sel_hi:[1,0,1]
	v_pk_fma_f32 v[104:105], v[104:105], 0.5, v[110:111] op_sel_hi:[1,0,1]
	global_store_dwordx4 v[116:117], v[104:107], off offset:64 nt
	s_nop 1
	v_lshlrev_b32_e32 v106, 16, v164
	v_and_b32_e32 v107, 0xffff0000, v164
	v_lshlrev_b32_e32 v104, 16, v165
	v_and_b32_e32 v105, 0xffff0000, v165
	v_pk_fma_f32 v[102:103], v[102:103], 0.5, v[104:105] op_sel_hi:[1,0,1]
	v_pk_fma_f32 v[100:101], v[100:101], 0.5, v[106:107] op_sel_hi:[1,0,1]
	global_store_dwordx4 v[116:117], v[100:103], off offset:512 nt
	s_nop 1
	v_lshlrev_b32_e32 v106, 16, v166
	v_add_u32_e32 v102, 32, v144
	v_ashrrev_i32_e32 v103, 31, v102
	v_lshlrev_b64 v[102:103], 10, v[102:103]
	v_and_b32_e32 v107, 0xffff0000, v166
	v_lshlrev_b32_e32 v100, 16, v167
	v_and_b32_e32 v101, 0xffff0000, v167
	v_lshl_add_u64 v[102:103], v[102:103], 0, v[146:147]
	v_pk_fma_f32 v[94:95], v[94:95], 0.5, v[100:101] op_sel_hi:[1,0,1]
	v_pk_fma_f32 v[92:93], v[92:93], 0.5, v[106:107] op_sel_hi:[1,0,1]
	v_lshl_add_u64 v[104:105], v[102:103], 1, s[8:9]
	global_store_dwordx4 v[116:117], v[92:95], off offset:576 nt
	global_load_dwordx2 v[92:93], v[104:105], off
	global_load_dwordx2 v[162:163], v[104:105], off offset:32
	global_load_dwordx2 v[164:165], v[104:105], off offset:256
	global_load_dwordx2 v[166:167], v[104:105], off offset:288
	v_lshl_add_u64 v[100:101], v[102:103], 2, s[76:77]
	s_waitcnt vmcnt(0)
	v_lshlrev_b32_e32 v102, 16, v92
	v_and_b32_e32 v103, 0xffff0000, v92
	v_lshlrev_b32_e32 v92, 16, v93
	v_and_b32_e32 v93, 0xffff0000, v93
	v_pk_fma_f32 v[94:95], v[98:99], 0.5, v[92:93] op_sel_hi:[1,0,1]
	v_pk_fma_f32 v[92:93], v[96:97], 0.5, v[102:103] op_sel_hi:[1,0,1]
	global_store_dwordx4 v[100:101], v[92:95], off nt
	s_nop 1
	v_lshlrev_b32_e32 v94, 16, v162
	v_and_b32_e32 v95, 0xffff0000, v162
	v_lshlrev_b32_e32 v92, 16, v163
	v_and_b32_e32 v93, 0xffff0000, v163
	v_pk_fma_f32 v[90:91], v[90:91], 0.5, v[92:93] op_sel_hi:[1,0,1]
	v_pk_fma_f32 v[88:89], v[88:89], 0.5, v[94:95] op_sel_hi:[1,0,1]
	global_store_dwordx4 v[100:101], v[88:91], off offset:64 nt
	s_nop 1
	v_lshlrev_b32_e32 v90, 16, v164
	v_and_b32_e32 v91, 0xffff0000, v164
	v_lshlrev_b32_e32 v88, 16, v165
	v_and_b32_e32 v89, 0xffff0000, v165
	v_pk_fma_f32 v[86:87], v[86:87], 0.5, v[88:89] op_sel_hi:[1,0,1]
	v_pk_fma_f32 v[84:85], v[84:85], 0.5, v[90:91] op_sel_hi:[1,0,1]
	global_store_dwordx4 v[100:101], v[84:87], off offset:512 nt
	s_nop 1
	v_lshlrev_b32_e32 v90, 16, v166
	v_add_u32_e32 v86, 48, v144
	v_ashrrev_i32_e32 v87, 31, v86
	v_lshlrev_b64 v[86:87], 10, v[86:87]
	v_and_b32_e32 v91, 0xffff0000, v166
	v_lshlrev_b32_e32 v84, 16, v167
	v_and_b32_e32 v85, 0xffff0000, v167
	v_lshl_add_u64 v[86:87], v[86:87], 0, v[146:147]
	v_pk_fma_f32 v[78:79], v[78:79], 0.5, v[84:85] op_sel_hi:[1,0,1]
	v_pk_fma_f32 v[76:77], v[76:77], 0.5, v[90:91] op_sel_hi:[1,0,1]
	v_lshl_add_u64 v[88:89], v[86:87], 1, s[8:9]
	global_store_dwordx4 v[100:101], v[76:79], off offset:576 nt
	global_load_dwordx2 v[76:77], v[88:89], off
	global_load_dwordx2 v[162:163], v[88:89], off offset:32
	global_load_dwordx2 v[164:165], v[88:89], off offset:256
	global_load_dwordx2 v[166:167], v[88:89], off offset:288
	v_lshl_add_u64 v[84:85], v[86:87], 2, s[76:77]
	s_waitcnt vmcnt(0)
	v_lshlrev_b32_e32 v86, 16, v76
	v_and_b32_e32 v87, 0xffff0000, v76
	v_lshlrev_b32_e32 v76, 16, v77
	v_and_b32_e32 v77, 0xffff0000, v77
	v_pk_fma_f32 v[78:79], v[82:83], 0.5, v[76:77] op_sel_hi:[1,0,1]
	v_pk_fma_f32 v[76:77], v[80:81], 0.5, v[86:87] op_sel_hi:[1,0,1]
	global_store_dwordx4 v[84:85], v[76:79], off nt
	s_nop 1
	v_lshlrev_b32_e32 v78, 16, v162
	v_and_b32_e32 v79, 0xffff0000, v162
	v_lshlrev_b32_e32 v76, 16, v163
	v_and_b32_e32 v77, 0xffff0000, v163
	v_pk_fma_f32 v[74:75], v[74:75], 0.5, v[76:77] op_sel_hi:[1,0,1]
	v_pk_fma_f32 v[72:73], v[72:73], 0.5, v[78:79] op_sel_hi:[1,0,1]
	global_store_dwordx4 v[84:85], v[72:75], off offset:64 nt
	s_nop 1
	v_lshlrev_b32_e32 v74, 16, v164
	v_and_b32_e32 v75, 0xffff0000, v164
	v_lshlrev_b32_e32 v72, 16, v165
	v_and_b32_e32 v73, 0xffff0000, v165
	v_pk_fma_f32 v[70:71], v[70:71], 0.5, v[72:73] op_sel_hi:[1,0,1]
	v_pk_fma_f32 v[68:69], v[68:69], 0.5, v[74:75] op_sel_hi:[1,0,1]
	global_store_dwordx4 v[84:85], v[68:71], off offset:512 nt
	s_nop 1
	v_lshlrev_b32_e32 v74, 16, v166
	v_add_u32_e32 v70, 0x80, v144
	v_ashrrev_i32_e32 v71, 31, v70
	v_lshlrev_b64 v[70:71], 10, v[70:71]
	v_and_b32_e32 v75, 0xffff0000, v166
	v_lshlrev_b32_e32 v68, 16, v167
	v_and_b32_e32 v69, 0xffff0000, v167
	v_lshl_add_u64 v[70:71], v[70:71], 0, v[146:147]
	v_pk_fma_f32 v[66:67], v[66:67], 0.5, v[68:69] op_sel_hi:[1,0,1]
	v_pk_fma_f32 v[64:65], v[64:65], 0.5, v[74:75] op_sel_hi:[1,0,1]
	v_lshl_add_u64 v[72:73], v[70:71], 1, s[8:9]
	global_store_dwordx4 v[84:85], v[64:67], off offset:576 nt
	global_load_dwordx2 v[64:65], v[72:73], off
	global_load_dwordx2 v[162:163], v[72:73], off offset:32
	global_load_dwordx2 v[164:165], v[72:73], off offset:256
	global_load_dwordx2 v[166:167], v[72:73], off offset:288
	s_waitcnt vmcnt(0)
	v_lshlrev_b32_e32 v68, 16, v64
	v_and_b32_e32 v69, 0xffff0000, v64
	v_lshlrev_b32_e32 v64, 16, v65
	v_and_b32_e32 v65, 0xffff0000, v65
	v_lshl_add_u64 v[66:67], v[70:71], 2, s[76:77]
	v_pk_fma_f32 v[62:63], v[62:63], 0.5, v[64:65] op_sel_hi:[1,0,1]
	v_pk_fma_f32 v[60:61], v[60:61], 0.5, v[68:69] op_sel_hi:[1,0,1]
	global_store_dwordx4 v[66:67], v[60:63], off nt
	s_nop 1
	v_lshlrev_b32_e32 v62, 16, v162
	v_and_b32_e32 v63, 0xffff0000, v162
	v_lshlrev_b32_e32 v60, 16, v163
	v_and_b32_e32 v61, 0xffff0000, v163
	v_pk_fma_f32 v[58:59], v[58:59], 0.5, v[60:61] op_sel_hi:[1,0,1]
	v_pk_fma_f32 v[56:57], v[56:57], 0.5, v[62:63] op_sel_hi:[1,0,1]
	global_store_dwordx4 v[66:67], v[56:59], off offset:64 nt
	s_nop 1
	v_lshlrev_b32_e32 v58, 16, v164
	v_and_b32_e32 v59, 0xffff0000, v164
	v_lshlrev_b32_e32 v56, 16, v165
	v_and_b32_e32 v57, 0xffff0000, v165
	v_pk_fma_f32 v[54:55], v[54:55], 0.5, v[56:57] op_sel_hi:[1,0,1]
	v_pk_fma_f32 v[52:53], v[52:53], 0.5, v[58:59] op_sel_hi:[1,0,1]
	global_store_dwordx4 v[66:67], v[52:55], off offset:512 nt
	s_nop 1
	v_lshlrev_b32_e32 v58, 16, v166
	v_add_u32_e32 v54, 0x90, v144
	v_ashrrev_i32_e32 v55, 31, v54
	v_lshlrev_b64 v[54:55], 10, v[54:55]
	v_and_b32_e32 v59, 0xffff0000, v166
	v_lshlrev_b32_e32 v52, 16, v167
	v_and_b32_e32 v53, 0xffff0000, v167
	v_lshl_add_u64 v[54:55], v[54:55], 0, v[146:147]
	v_pk_fma_f32 v[46:47], v[46:47], 0.5, v[52:53] op_sel_hi:[1,0,1]
	v_pk_fma_f32 v[44:45], v[44:45], 0.5, v[58:59] op_sel_hi:[1,0,1]
	v_lshl_add_u64 v[56:57], v[54:55], 1, s[8:9]
	global_store_dwordx4 v[66:67], v[44:47], off offset:576 nt
	global_load_dwordx2 v[44:45], v[56:57], off
	global_load_dwordx2 v[162:163], v[56:57], off offset:32
	global_load_dwordx2 v[164:165], v[56:57], off offset:256
	global_load_dwordx2 v[166:167], v[56:57], off offset:288
	v_lshl_add_u64 v[52:53], v[54:55], 2, s[76:77]
	s_waitcnt vmcnt(0)
	v_lshlrev_b32_e32 v54, 16, v44
	v_and_b32_e32 v55, 0xffff0000, v44
	v_lshlrev_b32_e32 v44, 16, v45
	v_and_b32_e32 v45, 0xffff0000, v45
	v_pk_fma_f32 v[46:47], v[50:51], 0.5, v[44:45] op_sel_hi:[1,0,1]
	v_pk_fma_f32 v[44:45], v[48:49], 0.5, v[54:55] op_sel_hi:[1,0,1]
	global_store_dwordx4 v[52:53], v[44:47], off nt
	s_nop 1
	v_lshlrev_b32_e32 v46, 16, v162
	v_and_b32_e32 v47, 0xffff0000, v162
	v_lshlrev_b32_e32 v44, 16, v163
	v_and_b32_e32 v45, 0xffff0000, v163
	v_pk_fma_f32 v[42:43], v[42:43], 0.5, v[44:45] op_sel_hi:[1,0,1]
	v_pk_fma_f32 v[40:41], v[40:41], 0.5, v[46:47] op_sel_hi:[1,0,1]
	global_store_dwordx4 v[52:53], v[40:43], off offset:64 nt
	s_nop 1
	v_lshlrev_b32_e32 v42, 16, v164
	v_and_b32_e32 v43, 0xffff0000, v164
	v_lshlrev_b32_e32 v40, 16, v165
	v_and_b32_e32 v41, 0xffff0000, v165
	v_pk_fma_f32 v[38:39], v[38:39], 0.5, v[40:41] op_sel_hi:[1,0,1]
	v_pk_fma_f32 v[36:37], v[36:37], 0.5, v[42:43] op_sel_hi:[1,0,1]
	global_store_dwordx4 v[52:53], v[36:39], off offset:512 nt
	s_nop 1
	v_lshlrev_b32_e32 v42, 16, v166
	v_add_u32_e32 v38, 0xa0, v144
	v_ashrrev_i32_e32 v39, 31, v38
	v_lshlrev_b64 v[38:39], 10, v[38:39]
	v_and_b32_e32 v43, 0xffff0000, v166
	v_lshlrev_b32_e32 v36, 16, v167
	v_and_b32_e32 v37, 0xffff0000, v167
	v_lshl_add_u64 v[38:39], v[38:39], 0, v[146:147]
	v_pk_fma_f32 v[30:31], v[30:31], 0.5, v[36:37] op_sel_hi:[1,0,1]
	v_pk_fma_f32 v[28:29], v[28:29], 0.5, v[42:43] op_sel_hi:[1,0,1]
	v_lshl_add_u64 v[40:41], v[38:39], 1, s[8:9]
	global_store_dwordx4 v[52:53], v[28:31], off offset:576 nt
	global_load_dwordx2 v[28:29], v[40:41], off
	global_load_dwordx2 v[162:163], v[40:41], off offset:32
	global_load_dwordx2 v[164:165], v[40:41], off offset:256
	global_load_dwordx2 v[166:167], v[40:41], off offset:288
	v_lshl_add_u64 v[36:37], v[38:39], 2, s[76:77]
	s_waitcnt vmcnt(0)
	v_lshlrev_b32_e32 v38, 16, v28
	v_and_b32_e32 v39, 0xffff0000, v28
	v_lshlrev_b32_e32 v28, 16, v29
	v_and_b32_e32 v29, 0xffff0000, v29
	v_pk_fma_f32 v[30:31], v[34:35], 0.5, v[28:29] op_sel_hi:[1,0,1]
	v_pk_fma_f32 v[28:29], v[32:33], 0.5, v[38:39] op_sel_hi:[1,0,1]
	global_store_dwordx4 v[36:37], v[28:31], off nt
	s_nop 1
	v_lshlrev_b32_e32 v30, 16, v162
	v_and_b32_e32 v31, 0xffff0000, v162
	v_lshlrev_b32_e32 v28, 16, v163
	v_and_b32_e32 v29, 0xffff0000, v163
	v_pk_fma_f32 v[26:27], v[26:27], 0.5, v[28:29] op_sel_hi:[1,0,1]
	v_pk_fma_f32 v[24:25], v[24:25], 0.5, v[30:31] op_sel_hi:[1,0,1]
	global_store_dwordx4 v[36:37], v[24:27], off offset:64 nt
	s_nop 1
	v_lshlrev_b32_e32 v26, 16, v164
	v_and_b32_e32 v27, 0xffff0000, v164
	v_lshlrev_b32_e32 v24, 16, v165
	v_and_b32_e32 v25, 0xffff0000, v165
	v_pk_fma_f32 v[22:23], v[22:23], 0.5, v[24:25] op_sel_hi:[1,0,1]
	v_pk_fma_f32 v[20:21], v[20:21], 0.5, v[26:27] op_sel_hi:[1,0,1]
	global_store_dwordx4 v[36:37], v[20:23], off offset:512 nt
	s_nop 1
	v_lshlrev_b32_e32 v26, 16, v166
	v_add_u32_e32 v22, 0xb0, v144
	v_ashrrev_i32_e32 v23, 31, v22
	v_lshlrev_b64 v[22:23], 10, v[22:23]
	v_and_b32_e32 v27, 0xffff0000, v166
	v_lshlrev_b32_e32 v20, 16, v167
	v_and_b32_e32 v21, 0xffff0000, v167
	v_lshl_add_u64 v[22:23], v[22:23], 0, v[146:147]
	v_pk_fma_f32 v[14:15], v[14:15], 0.5, v[20:21] op_sel_hi:[1,0,1]
	v_pk_fma_f32 v[12:13], v[12:13], 0.5, v[26:27] op_sel_hi:[1,0,1]
	v_lshl_add_u64 v[24:25], v[22:23], 1, s[8:9]
	global_store_dwordx4 v[36:37], v[12:15], off offset:576 nt
	global_load_dwordx2 v[12:13], v[24:25], off
	global_load_dwordx2 v[162:163], v[24:25], off offset:32
	global_load_dwordx2 v[164:165], v[24:25], off offset:256
	global_load_dwordx2 v[166:167], v[24:25], off offset:288
	v_lshl_add_u64 v[20:21], v[22:23], 2, s[76:77]
	s_waitcnt vmcnt(0)
	v_lshlrev_b32_e32 v22, 16, v12
	v_and_b32_e32 v23, 0xffff0000, v12
	v_lshlrev_b32_e32 v12, 16, v13
	v_and_b32_e32 v13, 0xffff0000, v13
	v_pk_fma_f32 v[14:15], v[18:19], 0.5, v[12:13] op_sel_hi:[1,0,1]
	v_pk_fma_f32 v[12:13], v[16:17], 0.5, v[22:23] op_sel_hi:[1,0,1]
	global_store_dwordx4 v[20:21], v[12:15], off nt
	s_nop 1
	v_lshlrev_b32_e32 v14, 16, v162
	v_and_b32_e32 v15, 0xffff0000, v162
	v_lshlrev_b32_e32 v12, 16, v163
	v_and_b32_e32 v13, 0xffff0000, v163
	v_pk_fma_f32 v[10:11], v[10:11], 0.5, v[12:13] op_sel_hi:[1,0,1]
	v_pk_fma_f32 v[8:9], v[8:9], 0.5, v[14:15] op_sel_hi:[1,0,1]
	global_store_dwordx4 v[20:21], v[8:11], off offset:64 nt
	s_nop 1
	v_lshlrev_b32_e32 v10, 16, v164
	v_and_b32_e32 v11, 0xffff0000, v164
	v_lshlrev_b32_e32 v8, 16, v165
	v_and_b32_e32 v9, 0xffff0000, v165
	v_pk_fma_f32 v[6:7], v[6:7], 0.5, v[8:9] op_sel_hi:[1,0,1]
	v_pk_fma_f32 v[4:5], v[4:5], 0.5, v[10:11] op_sel_hi:[1,0,1]
	global_store_dwordx4 v[20:21], v[4:7], off offset:512 nt
	s_nop 1
	v_lshlrev_b32_e32 v6, 16, v166
	v_and_b32_e32 v7, 0xffff0000, v166
	v_lshlrev_b32_e32 v4, 16, v167
	v_and_b32_e32 v5, 0xffff0000, v167
	v_pk_fma_f32 v[2:3], v[2:3], 0.5, v[4:5] op_sel_hi:[1,0,1]
	v_pk_fma_f32 v[0:1], v[0:1], 0.5, v[6:7] op_sel_hi:[1,0,1]
	global_store_dwordx4 v[20:21], v[0:3], off offset:576 nt
	s_cbranch_vccnz .LBB0_1457
	s_andn2_b64 vcc, exec, s[10:11]
	s_cbranch_vccnz .LBB0_1456
	s_barrier
	s_branch .LBB0_1456
